# v8 with iteration-capped group-barrier spin and census/grid-guarded stagger delay
# speedup vs baseline: 1.0004x; 1.0004x over previous
; __device__ __forceinline__ unsigned xb_ld(unsigned* p)              { return __hip_atomic_load(p, __ATOMIC_RELAXED, __HIP_MEMORY_SCOPE_AGENT); }
; __device__ __forceinline__ unsigned xb_add(unsigned* p, unsigned v) { return __hip_atomic_fetch_add(p, v, __ATOMIC_RELAXED, __HIP_MEMORY_SCOPE_AGENT); }
; #define XB_SPIN(cond, bar) do { unsigned _sp = 0; while (cond) { __builtin_amdgcn_s_sleep(1); \
;     if ((++_sp & 255u) == 0u) { if (xb_ld(&(bar)[XB_TMO])) break; if (_sp > XB_SPIN_CAP) { atomicAdd(&(bar)[XB_TMO], 1u); break; } } } } while (0)
; __device__ __forceinline__ void xcd_barrier(const XcdBarrier& b) {
;     asm volatile("s_waitcnt vmcnt(0)" ::: "memory");
;     __syncthreads();
;     if (threadIdx.x == 0) {
;         unsigned* bar = b.bar;
;         __builtin_amdgcn_s_waitcnt(0);
;         unsigned nloc = b.st[0], nx = b.st[1];
;         if (nloc == 0u) { xcd_barrier_complete(bar, b.x, nloc, nx); b.st[0] = nloc; b.st[1] = nx; }
;         const unsigned old = xb_add(&bar[XB_XSUB(b.x)], 1u);
;         const unsigned gen = old / nloc;
;         if (old + 1u == (gen + 1u) * nloc) {
;             __builtin_amdgcn_fence(__ATOMIC_RELEASE, "agent");
;             asm volatile("s_waitcnt vmcnt(0)" ::: "memory");
;             const unsigned og = xb_add(&bar[XB_TOP], 1u);
;             const unsigned tg = og / nx;
;             if (og + 1u == (tg + 1u) * nx) xb_add(&bar[XB_TOPGEN], 1u);
;             else XB_SPIN(xb_ld(&bar[XB_TOPGEN]) == tg, bar);
;             __builtin_amdgcn_fence(__ATOMIC_ACQUIRE, "agent");
;             xb_add(&bar[XB_XGEN(b.x)], 1u);
;             asm volatile("s_waitcnt vmcnt(0)" ::: "memory");
;         } else {
;             XB_SPIN(xb_ld(&bar[XB_XGEN(b.x)]) == gen, bar);
;             __builtin_amdgcn_fence(__ATOMIC_ACQUIRE, "agent");
;             asm volatile("s_waitcnt vmcnt(0)" ::: "memory");
;         }
;     }
;     __syncthreads();
.LBB0_823:
	s_waitcnt vmcnt(0)
	s_waitcnt lgkmcnt(0)
	s_barrier
	s_and_saveexec_b64 s[10:11], s[82:83]
	s_cbranch_execz .LBB0_875
	s_cmp_eq_u32 s99, 0
	s_cbranch_scc1 .Lgb0_orig
	s_cmpk_lg_u32 s30, 0x100
	s_cbranch_scc1 .Lgb0_orig
	s_and_b32 s12, s2, 7
	s_lshl_b32 s12, s12, 1
	s_bfe_u32 s13, s2, 0x10003
	s_or_b32 s12, s12, s13
	s_lshl_b32 s12, s12, 6
	s_add_u32 s12, s12, 0x15000
	v_mov_b32_e32 v0, s12
	v_mov_b32_e32 v1, 1
	global_atomic_add v2, v0, v1, s[28:29] sc0
	s_waitcnt vmcnt(0)
	v_and_b32_e32 v4, 15, v2
	v_lshrrev_b32_e32 v2, 4, v2
	v_cmp_ne_u32_e32 vcc, 15, v4
	s_nop 1
	s_cbranch_vccnz .Lgb0_wait
	global_atomic_add v0, v1, s[28:29] offset:2048
	s_branch .Lgb0_done
.Lgb0_wait:
	s_mov_b32 s13, 0
.Lgb0_spin:
	global_load_dword v4, v0, s[28:29] offset:2048 sc1
	s_waitcnt vmcnt(0)
	v_cmp_gt_u32_e32 vcc, v4, v2
	s_nop 1
	s_cbranch_vccnz .Lgb0_done
	s_sleep 1
	s_add_i32 s13, s13, 1
	s_cmp_lt_u32 s13, 0x100000
	s_cbranch_scc1 .Lgb0_spin

; __device__ __forceinline__ unsigned xb_ld(unsigned* p)              { return __hip_atomic_load(p, __ATOMIC_RELAXED, __HIP_MEMORY_SCOPE_AGENT); }
; __device__ __forceinline__ unsigned xb_add(unsigned* p, unsigned v) { return __hip_atomic_fetch_add(p, v, __ATOMIC_RELAXED, __HIP_MEMORY_SCOPE_AGENT); }
; #define XB_SPIN(cond, bar) do { unsigned _sp = 0; while (cond) { __builtin_amdgcn_s_sleep(1); \
;     if ((++_sp & 255u) == 0u) { if (xb_ld(&(bar)[XB_TMO])) break; if (_sp > XB_SPIN_CAP) { atomicAdd(&(bar)[XB_TMO], 1u); break; } } } } while (0)
; __device__ __forceinline__ void xcd_barrier(const XcdBarrier& b) {
;     asm volatile("s_waitcnt vmcnt(0)" ::: "memory");
;     __syncthreads();
;     if (threadIdx.x == 0) {
;         unsigned* bar = b.bar;
;         __builtin_amdgcn_s_waitcnt(0);
;         unsigned nloc = b.st[0], nx = b.st[1];
;         if (nloc == 0u) { xcd_barrier_complete(bar, b.x, nloc, nx); b.st[0] = nloc; b.st[1] = nx; }
;         const unsigned old = xb_add(&bar[XB_XSUB(b.x)], 1u);
;         const unsigned gen = old / nloc;
;         if (old + 1u == (gen + 1u) * nloc) {
;             __builtin_amdgcn_fence(__ATOMIC_RELEASE, "agent");
;             asm volatile("s_waitcnt vmcnt(0)" ::: "memory");
;             const unsigned og = xb_add(&bar[XB_TOP], 1u);
;             const unsigned tg = og / nx;
;             if (og + 1u == (tg + 1u) * nx) xb_add(&bar[XB_TOPGEN], 1u);
;             else XB_SPIN(xb_ld(&bar[XB_TOPGEN]) == tg, bar);
;             __builtin_amdgcn_fence(__ATOMIC_ACQUIRE, "agent");
;             xb_add(&bar[XB_XGEN(b.x)], 1u);
;             asm volatile("s_waitcnt vmcnt(0)" ::: "memory");
;         } else {
;             XB_SPIN(xb_ld(&bar[XB_XGEN(b.x)]) == gen, bar);
;             __builtin_amdgcn_fence(__ATOMIC_ACQUIRE, "agent");
;             asm volatile("s_waitcnt vmcnt(0)" ::: "memory");
;         }
;     }
;     __syncthreads();
.LBB0_1025:
	s_waitcnt vmcnt(0)
	s_waitcnt vmcnt(0) lgkmcnt(0)
	s_barrier
	s_and_saveexec_b64 s[10:11], s[82:83]
	s_cbranch_execz .LBB0_1077
	s_cmp_eq_u32 s99, 0
	s_cbranch_scc1 .Lgb2_orig
	s_cmpk_lg_u32 s30, 0x100
	s_cbranch_scc1 .Lgb2_orig
	s_and_b32 s12, s2, 7
	s_lshl_b32 s12, s12, 1
	s_bfe_u32 s13, s2, 0x10003
	s_or_b32 s12, s12, s13
	s_lshl_b32 s12, s12, 6
	s_add_u32 s12, s12, 0x15000
	v_mov_b32_e32 v0, s12
	v_mov_b32_e32 v1, 1
	global_atomic_add v2, v0, v1, s[28:29] sc0
	s_waitcnt vmcnt(0)
	v_and_b32_e32 v4, 15, v2
	v_lshrrev_b32_e32 v2, 4, v2
	v_cmp_ne_u32_e32 vcc, 15, v4
	s_nop 1
	s_cbranch_vccnz .Lgb2_wait
	global_atomic_add v0, v1, s[28:29] offset:2048
	s_branch .Lgb2_done
